# attention second sub-tile: staging writes start before the map-1 converts and finish by the fourth map-1 PV MFMA
# baseline (speedup 1.0000x reference)
; #define LAS __attribute__((address_space(3)))
; #define AT_RAISE(MP) do { if (trig[MP]) { const float dl = fmaxf(__builtin_amdgcn_logf(pmx[MP]), 0.f), al = __builtin_amdgcn_exp2f(-dl); mref[MP] += dl; lsum[MP] *= al; \
;                 _Pragma("unroll") for (int cb = 0; cb < 4; ++cb) o[MP][cb] = o[MP][cb] * al; } } while (0)
; __device__ __forceinline__ void dattn_unit(LAS unsigned char* lds, int b, int h, int qb, const bf16* Q, const bf16* K, const bf16* V, bf16* YB, float lam, const float* subg, float oml, int tid) {
;     ...
;             for (int cb = 0; cb < 4; ++cb) { const LAS bf16* vp = Vt + (32 * cb + ql) * 72 + 32 * sub + 4 * hi;
;                 const v2u a0 = *(const LAS v2u*)(vp), a1 = *(const LAS v2u*)(vp + 8), a2 = *(const LAS v2u*)(vp + 16), a3 = *(const LAS v2u*)(vp + 24);
;                 const v4u f0 = {a0.x, a0.y, a1.x, a1.y}, f1 = {a2.x, a2.y, a3.x, a3.y};
;                 o[0][cb] = __builtin_amdgcn_mfma_f32_32x32x16_bf16(__builtin_bit_cast(bf16x8, f0), pA0, o[0][cb], 0, 0, 0);
;                 o[1][cb] = __builtin_amdgcn_mfma_f32_32x32x16_bf16(__builtin_bit_cast(bf16x8, f0), pA1, o[1][cb], 0, 0, 0);
;                 o[0][cb] = __builtin_amdgcn_mfma_f32_32x32x16_bf16(__builtin_bit_cast(bf16x8, f1), pB0, o[0][cb], 0, 0, 0);
;                 o[1][cb] = __builtin_amdgcn_mfma_f32_32x32x16_bf16(__builtin_bit_cast(bf16x8, f1), pB1, o[1][cb], 0, 0, 0); }
;             AT_RAISE(0); AT_RAISE(1);
.LBB0_245:
	s_xor_b32 s18, s38, 0x9000
	v_add3_u32 v148, s18, v196, v180
	v_add3_u32 v149, s18, v197, v195
	s_waitcnt vmcnt(3)
	ds_write_b128 v148, v[168:171]
	v_cvt_pk_bf16_f32 v152, v155, v129
	v_cvt_pk_bf16_f32 v153, v130, v131
	v_cvt_pk_bf16_f32 v154, v132, v156
	v_cvt_pk_bf16_f32 v155, v157, v158
	s_waitcnt vmcnt(2)
	ds_write_b128 v148, v[172:175] offset:9216
	v_cvt_pk_bf16_f32 v130, v133, v134
	v_cvt_pk_bf16_f32 v131, v135, v136
	v_cvt_pk_bf16_f32 v132, v137, v138
	v_cvt_pk_bf16_f32 v133, v139, v140
	s_andn2_b64 vcc, exec, s[48:49]
	s_nop 0
	v_mfma_f32_32x32x16_bf16 v[64:79], v[222:225], v[152:155], v[64:79]
	s_waitcnt vmcnt(1)
	ds_write_b16 v149, v164 offset:18432
	ds_write_b16_d16_hi v149, v164 offset:18576
	ds_write_b16 v149, v165 offset:18720
	ds_write_b16_d16_hi v149, v165 offset:18864
	v_mfma_f32_32x32x16_bf16 v[64:79], v[226:229], v[130:133], v[64:79]
	ds_write_b16 v149, v166 offset:19008
	ds_write_b16_d16_hi v149, v166 offset:19152
	ds_write_b16 v149, v167 offset:19296
	ds_write_b16_d16_hi v149, v167 offset:19440
	v_mfma_f32_32x32x16_bf16 v[32:47], v[230:233], v[152:155], v[32:47]
	s_waitcnt vmcnt(0)
	ds_write_b16 v149, v160 offset:19584
	ds_write_b16_d16_hi v149, v160 offset:19728
	ds_write_b16 v149, v161 offset:19872
	ds_write_b16_d16_hi v149, v161 offset:20016
	v_mfma_f32_32x32x16_bf16 v[32:47], v[234:237], v[130:133], v[32:47]
	ds_write_b16 v149, v162 offset:20160
	ds_write_b16_d16_hi v149, v162 offset:20304
	ds_write_b16 v149, v163 offset:20448
	ds_write_b16_d16_hi v149, v163 offset:20592
	v_mfma_f32_32x32x16_bf16 v[96:111], v[212:215], v[152:155], v[96:111]
	v_mfma_f32_32x32x16_bf16 v[96:111], v[200:203], v[130:133], v[96:111]
	v_mfma_f32_32x32x16_bf16 v[0:15], v[238:241], v[152:155], v[0:15]
	s_nop 0
	v_mfma_f32_32x32x16_bf16 v[0:15], v[218:221], v[130:133], v[0:15]
	s_cbranch_vccnz .LBB0_247
	v_log_f32_e32 v129, v146
	s_nop 0
	v_max_f32_e32 v129, 0, v129
	v_exp_f32_e64 v130, -v129
	v_add_f32_e32 v190, v190, v129
	s_nop 1
	v_pk_mul_f32 v[126:127], v[130:131], v[126:127] op_sel_hi:[0,1]
	v_pk_mul_f32 v[124:125], v[130:131], v[124:125] op_sel_hi:[0,1]
	v_pk_mul_f32 v[122:123], v[130:131], v[122:123] op_sel_hi:[0,1]
	v_pk_mul_f32 v[120:121], v[130:131], v[120:121] op_sel_hi:[0,1]
	v_pk_mul_f32 v[118:119], v[130:131], v[118:119] op_sel_hi:[0,1]
	v_pk_mul_f32 v[116:117], v[130:131], v[116:117] op_sel_hi:[0,1]
	v_pk_mul_f32 v[114:115], v[130:131], v[114:115] op_sel_hi:[0,1]
	v_pk_mul_f32 v[112:113], v[130:131], v[112:113] op_sel_hi:[0,1]
	v_pk_mul_f32 v[94:95], v[130:131], v[94:95] op_sel_hi:[0,1]
	v_pk_mul_f32 v[92:93], v[130:131], v[92:93] op_sel_hi:[0,1]
	v_pk_mul_f32 v[90:91], v[130:131], v[90:91] op_sel_hi:[0,1]
	v_pk_mul_f32 v[88:89], v[130:131], v[88:89] op_sel_hi:[0,1]
	v_pk_mul_f32 v[86:87], v[130:131], v[86:87] op_sel_hi:[0,1]
	v_pk_mul_f32 v[84:85], v[130:131], v[84:85] op_sel_hi:[0,1]
	v_pk_mul_f32 v[82:83], v[130:131], v[82:83] op_sel_hi:[0,1]
	v_pk_mul_f32 v[80:81], v[130:131], v[80:81] op_sel_hi:[0,1]
	v_pk_mul_f32 v[62:63], v[130:131], v[62:63] op_sel_hi:[0,1]
	v_pk_mul_f32 v[60:61], v[130:131], v[60:61] op_sel_hi:[0,1]
	v_pk_mul_f32 v[58:59], v[130:131], v[58:59] op_sel_hi:[0,1]
	v_pk_mul_f32 v[56:57], v[130:131], v[56:57] op_sel_hi:[0,1]
	v_pk_mul_f32 v[54:55], v[130:131], v[54:55] op_sel_hi:[0,1]
	v_pk_mul_f32 v[52:53], v[130:131], v[52:53] op_sel_hi:[0,1]
	v_pk_mul_f32 v[50:51], v[130:131], v[50:51] op_sel_hi:[0,1]
	v_pk_mul_f32 v[48:49], v[130:131], v[48:49] op_sel_hi:[0,1]
	v_pk_mul_f32 v[30:31], v[130:131], v[30:31] op_sel_hi:[0,1]
	v_pk_mul_f32 v[28:29], v[130:131], v[28:29] op_sel_hi:[0,1]
	v_pk_mul_f32 v[26:27], v[130:131], v[26:27] op_sel_hi:[0,1]
	v_pk_mul_f32 v[24:25], v[130:131], v[24:25] op_sel_hi:[0,1]
	v_pk_mul_f32 v[22:23], v[130:131], v[22:23] op_sel_hi:[0,1]
	v_pk_mul_f32 v[20:21], v[130:131], v[20:21] op_sel_hi:[0,1]
	v_pk_mul_f32 v[18:19], v[130:131], v[18:19] op_sel_hi:[0,1]
	v_pk_mul_f32 v[16:17], v[130:131], v[16:17] op_sel_hi:[0,1]
	v_mul_f32_e32 v179, v179, v130
